# attnA: static s_setprio 1 for waves 4-7 across the tile loop
# speedup vs baseline: 1.0107x; 1.0073x over previous
; #define FLAS __attribute__((address_space(3)))
; #define FA_SB() __builtin_amdgcn_sched_barrier(0)
; __device__ __forceinline__ void attn_unit_a(FLAS unsigned char* lds, const Unit u) {
;     ...
;     const f32x16 z16 = {0.f,0.f,0.f,0.f,0.f,0.f,0.f,0.f,0.f,0.f,0.f,0.f,0.f,0.f,0.f,0.f};
;     f32x16 o[NDB];
; #pragma unroll
;     for (int i = 0; i < NDB; ++i) o[i] = z16;
;     float mrun = 0.f, lsum = 0.f, fpend = 1.f; bool first = true, pend = false;
;     ...
;     f32x16 pa0, pa1, pb0, pb1; float cbC = 0.f;
;     { bool zi; FA_BIAS(0, pa0, pa1, cbC, zi); if (zi) { pa0 = z16; pa1 = z16; }
;       const FLAS unsigned char* kb = lds + LA_K;
; #pragma unroll
;       for (int d0 = 0; d0 < 4; ++d0) { const int ko = (2 * d0 + hi) * 1024 + ((r32 ^ (2 * d0 + hi)) * 16); const bf16x8 a0 = *(const FLAS bf16x8*)(kb + ko), a1 = *(const FLAS bf16x8*)(kb + ko + 512);
;           pa0 = __builtin_amdgcn_mfma_f32_32x32x16_bf16(a0, qr[d0], pa0, 0, 0, 0); pa1 = __builtin_amdgcn_mfma_f32_32x32x16_bf16(a1, qr[d0], pa1, 0, 0, 0); } }
;     u32x4 pwa[4] = {{0u,0u,0u,0u},{0u,0u,0u,0u},{0u,0u,0u,0u},{0u,0u,0u,0u}}, pwb[4] = {{0u,0u,0u,0u},{0u,0u,0u,0u},{0u,0u,0u,0u},{0u,0u,0u,0u}};
;     auto step = [&](const int i, f32x16& pC0, f32x16& pC1, f32x16& pN0, f32x16& pN1, u32x4 (&PWC)[4], u32x4 (&PWN)[4]) __attribute__((always_inline)) {
;         if (pend) {
; #pragma unroll
;             for (int d = 0; d < NDB; ++d) o[d] = o[d] * fpend;
;             pend = false; }
;         if (i + 2 < NT) { kreg = *(const u32x4*)(ksrc + (size_t)(u.t_lo + i + 2) * 64 * u.ldk);
; #pragma unroll
;             for (int j = 0; j < 2; ++j) vreg[j] = *(const u32x4*)(vsrc + (size_t)j * 64 * MTOK + (u.t_lo + i + 2) * 64); }
;         const int vsp = (i == 0) ? 0 : ((i - 1) & 3);
;         const FLAS unsigned char* vb_ = lds + LA_V + vsp * VBUF + r32 * VPITCH + hi * 16;
;         const FLAS unsigned char* kb = lds + LA_K + ((i + 1) & 1) * KBUF;
;     ...
;         u32x4 vr[3];
; #pragma unroll
;         for (int m = 0; m < 3; ++m) vr[m] = FA_VFRAG(m);
;         const float off = cbC - mrun;
;         FA_SB();
;         float ra, rb, rm;
;         FA_PVM(0); pC0[0] = fadd_s(pC0[0], off); pC1[0] = fadd_s(pC1[0], off); pC0[1] = fadd_s(pC0[1], off); pC1[1] = fadd_s(pC1[1], off); pC0[2] = fadd_s(pC0[2], off); pC1[2] = fadd_s(pC1[2], off); FA_SB();
.LBB0_432:
	v_xor_b32_e32 v1, v243, v5
	v_lshlrev_b32_e32 v1, 4, v1
	v_lshl_add_u32 v4, v243, 10, 0
	v_add_u32_e32 v247, v4, v1
	ds_read_b128 v[6:9], v247
	ds_read_b128 v[10:13], v247 offset:512
	v_or_b32_e32 v1, 2, v243
	v_bitop3_b32 v4, v243, v5, 2 bitop3:0x36
	v_lshlrev_b32_e32 v4, 4, v4
	v_lshl_add_u32 v1, v1, 10, 0
	v_add_u32_e32 v248, v1, v4
	s_waitcnt lgkmcnt(1)
	v_mfma_f32_32x32x16_bf16 v[128:143], v[6:9], v[160:163], v[128:143]
	ds_read_b128 v[6:9], v248
	v_or_b32_e32 v1, 4, v243
	v_bitop3_b32 v4, v243, v5, 4 bitop3:0x36
	v_lshlrev_b32_e32 v4, 4, v4
	v_lshl_add_u32 v1, v1, 10, 0
	v_add_u32_e32 v249, v1, v4
	s_lshr_b32 s0, s43, 8
	s_waitcnt lgkmcnt(1)
	v_mfma_f32_32x32x16_bf16 v[144:159], v[10:13], v[160:163], v[144:159]
	ds_read_b128 v[10:13], v248 offset:512
	s_lshl_b32 s15, s41, 1
	s_and_b32 s18, s40, 15
	s_and_b32 s0, s0, 1
	s_lshl_b32 s26, s42, 7
	s_bfe_u32 s1, s41, 0x2000d
	s_and_b32 s15, s15, 0xc000
	s_waitcnt lgkmcnt(1)
	v_mfma_f32_32x32x16_bf16 v[128:143], v[6:9], v[164:167], v[128:143]
	ds_read_b128 v[6:9], v249
	s_lshl_b32 s18, s18, 8
	s_lshl_b32 s20, s0, 7
	s_add_i32 s0, 0, 0x16000
	v_add_u32_e32 v240, s0, v224
	s_add_u32 s0, s70, s15
	s_mul_i32 s19, s1, 0x1800000
	s_waitcnt lgkmcnt(1)
	v_mfma_f32_32x32x16_bf16 v[144:159], v[10:13], v[164:167], v[144:159]
	ds_read_b128 v[10:13], v249 offset:512
	s_addc_u32 s1, s71, 0
	v_or_b32_e32 v1, 6, v243
	v_bitop3_b32 v4, v243, v5, 6 bitop3:0x36
	s_add_u32 s0, s0, s12
	v_lshlrev_b32_e32 v4, 4, v4
	v_lshl_add_u32 v1, v1, 10, 0
	s_waitcnt lgkmcnt(1)
	v_mfma_f32_32x32x16_bf16 v[128:143], v[6:9], v[168:171], v[128:143]
	s_addc_u32 s1, s1, 0
	v_add_u32_e32 v250, v1, v4
	v_lshl_add_u64 v[228:229], s[0:1], 0, v[2:3]
	s_lshl_b32 s0, s5, 8
	ds_read_b128 v[6:9], v250
	ds_read_b128 v[14:17], v250 offset:512
	s_and_b32 s0, s0, 0xfffff000
	s_or_b32 s0, s0, s18
	s_waitcnt lgkmcnt(2)
	v_mfma_f32_32x32x16_bf16 v[144:159], v[10:13], v[168:171], v[144:159]
	s_add_i32 s0, s0, s14
	s_sub_i32 s48, 64, s0
	v_add_lshl_u32 v1, s0, v5, 2
	s_add_u32 s0, s70, s20
	s_addc_u32 s1, s71, 0
	s_add_u32 s0, s0, s4
	s_addc_u32 s1, s1, 0
	s_waitcnt lgkmcnt(1)
	v_mfma_f32_32x32x16_bf16 v[128:143], v[6:9], v[172:175], v[128:143]
	s_add_u32 s0, s0, s19
	s_addc_u32 s1, s1, 0
	v_sub_u32_e32 v1, v224, v1
	v_mov_b64_e32 v[2:3], s[0:1]
	v_mul_u32_u24_e32 v246, 0x90, v5
	v_add_u32_e32 v210, 0, v1
	v_mad_i64_i32 v[230:231], s[0:1], v0, s65, v[2:3]
	s_waitcnt lgkmcnt(0)
	v_mfma_f32_32x32x16_bf16 v[144:159], v[14:17], v[172:175], v[144:159]
	v_mov_b32_e32 v14, v209
	v_mov_b32_e32 v15, v209
	v_mov_b32_e32 v0, v209
	v_mov_b32_e32 v1, v209
	v_mov_b32_e32 v2, v209
	v_mov_b32_e32 v3, v209
	v_mov_b32_e32 v4, v209
	v_mov_b32_e32 v5, v209
	v_mov_b32_e32 v6, v209
	v_mov_b32_e32 v7, v209
	v_mov_b32_e32 v8, v209
	v_mov_b32_e32 v9, v209
	v_mov_b32_e32 v10, v209
	v_mov_b32_e32 v11, v209
	v_mov_b32_e32 v12, v209
	v_mov_b32_e32 v13, v209
	v_mov_b32_e32 v188, 0
	v_mov_b64_e32 v[30:31], v[14:15]
	v_mov_b64_e32 v[46:47], v[14:15]
	v_mov_b64_e32 v[62:63], v[14:15]
	v_ashrrev_i32_e32 v223, 31, v222
	v_add3_u32 v251, 0, v246, v224
	s_mov_b32 s49, 0
	s_mov_b64 s[24:25], -1
	v_mov_b32_e32 v211, 0
	v_mov_b32_e32 v226, 1.0
	v_mov_b64_e32 v[28:29], v[12:13]
	v_mov_b64_e32 v[26:27], v[10:11]
	v_mov_b64_e32 v[24:25], v[8:9]
	v_mov_b64_e32 v[22:23], v[6:7]
	v_mov_b64_e32 v[20:21], v[4:5]
	v_mov_b64_e32 v[18:19], v[2:3]
	v_mov_b64_e32 v[16:17], v[0:1]
	v_mov_b64_e32 v[44:45], v[12:13]
	v_mov_b64_e32 v[42:43], v[10:11]
	v_mov_b64_e32 v[40:41], v[8:9]
	v_mov_b64_e32 v[38:39], v[6:7]
	v_mov_b64_e32 v[36:37], v[4:5]
	v_mov_b64_e32 v[34:35], v[2:3]
	v_mov_b64_e32 v[32:33], v[0:1]
	v_mov_b64_e32 v[60:61], v[12:13]
	v_mov_b64_e32 v[58:59], v[10:11]
	v_mov_b64_e32 v[56:57], v[8:9]
	v_mov_b64_e32 v[54:55], v[6:7]
	v_mov_b64_e32 v[52:53], v[4:5]
	v_mov_b64_e32 v[50:51], v[2:3]
	v_mov_b64_e32 v[48:49], v[0:1]
	s_mov_b32 s19, 0
	v_mov_b32_e32 v212, 0
	v_mov_b32_e32 v189, v188
	v_mov_b32_e32 v190, v188
	v_mov_b32_e32 v191, v188
	v_mov_b32_e32 v192, v188
	v_mov_b32_e32 v193, v188
	v_mov_b32_e32 v194, v188
	v_mov_b32_e32 v195, v188
	v_mov_b32_e32 v196, v188
	v_mov_b32_e32 v197, v188
	v_mov_b32_e32 v198, v188
	v_mov_b32_e32 v199, v188
	v_mov_b32_e32 v104, v188
	v_mov_b32_e32 v105, v188
	v_mov_b32_e32 v106, v188
	v_mov_b32_e32 v107, v188
	v_readfirstlane_b32 s100, v236
	s_nop 3
	s_cmp_lt_u32 s100, 0x100
	s_cbranch_scc1 .Lprio_skip
	s_setprio 1
.Lprio_skip:
	s_waitcnt lgkmcnt(0)
	v_readlane_b32 s100, v254, 47
	v_mov_b32_e32 v92, s13
	s_nop 3
	v_mov_b32_e32 v93, s100
	ds_read_b32 v92, v92
	ds_read_b32 v93, v93
	v_sub_f32_e32 v94, v204, v211
	v_add_f32_e32 v96, v128, v94
	v_add_f32_e32 v112, v144, v94
	v_add_f32_e32 v97, v129, v94
	v_add_f32_e32 v113, v145, v94
	v_add_f32_e32 v98, v130, v94
	v_add_f32_e32 v114, v146, v94
	v_add_f32_e32 v99, v131, v94
	v_add_f32_e32 v115, v147, v94
	v_add_f32_e32 v100, v132, v94
	v_add_f32_e32 v116, v148, v94
	v_add_f32_e32 v101, v133, v94
	v_add_f32_e32 v117, v149, v94
	v_add_f32_e32 v102, v134, v94
	v_add_f32_e32 v118, v150, v94
	v_add_f32_e32 v103, v135, v94
	v_add_f32_e32 v119, v151, v94
	v_add_f32_e32 v104, v136, v94
	v_add_f32_e32 v120, v152, v94
	v_add_f32_e32 v105, v137, v94
	v_add_f32_e32 v121, v153, v94
	v_add_f32_e32 v106, v138, v94
	v_add_f32_e32 v122, v154, v94
	v_add_f32_e32 v107, v139, v94
	v_add_f32_e32 v123, v155, v94
	v_add_f32_e32 v108, v140, v94
	v_add_f32_e32 v124, v156, v94
	v_add_f32_e32 v109, v141, v94
	v_add_f32_e32 v125, v157, v94
	v_add_f32_e32 v110, v142, v94
	v_add_f32_e32 v126, v158, v94
	v_add_f32_e32 v111, v143, v94
	v_add_f32_e32 v127, v159, v94
	v_mov_b32_e32 v144, 0x7fc00000
	v_mov_b32_e32 v145, 0x7fc00000
	v_mov_b32_e32 v146, 0x7fc00000
	v_mov_b32_e32 v147, 0x7fc00000
	v_mov_b32_e32 v148, 0x7fc00000
	v_mov_b32_e32 v149, 0x7fc00000
	v_mov_b32_e32 v150, 0x7fc00000
	v_mov_b32_e32 v151, 0x7fc00000
	v_mov_b32_e32 v152, 0x7fc00000
	v_mov_b32_e32 v153, 0x7fc00000
	v_mov_b32_e32 v154, 0x7fc00000
	v_mov_b32_e32 v155, 0x7fc00000
	v_mov_b32_e32 v156, 0x7fc00000
	v_mov_b32_e32 v157, 0x7fc00000
	v_mov_b32_e32 v158, 0x7fc00000
	v_mov_b32_e32 v159, 0x7fc00000
	v_mov_b32_e32 v204, 0
	v_mov_b32_e32 v205, 0
	v_mov_b32_e32 v206, 0
	v_mov_b32_e32 v207, 0
	s_waitcnt lgkmcnt(0)
	v_readfirstlane_b32 s101, v92
	v_readfirstlane_b32 s100, v93
	v_mov_b32_e32 v72, 0
	v_mov_b32_e32 v73, 0
	v_mov_b32_e32 v74, 0
	v_mov_b32_e32 v75, 0
	v_mov_b32_e32 v76, 0
	v_mov_b32_e32 v77, 0
	v_mov_b32_e32 v78, 0
	v_mov_b32_e32 v79, 0
	v_mov_b32_e32 v80, 0
	v_mov_b32_e32 v81, 0
	v_mov_b32_e32 v82, 0
	v_mov_b32_e32 v83, 0
	v_mov_b32_e32 v84, 0
	v_mov_b32_e32 v85, 0
	v_mov_b32_e32 v86, 0
	v_mov_b32_e32 v87, 0
	v_mov_b32_e32 v88, 0
	v_mov_b32_e32 v89, 0
	v_mov_b32_e32 v90, 0
	v_mov_b32_e32 v91, 0
	v_mov_b32_e32 v92, 0
	v_mov_b32_e32 v93, 0
	v_mov_b32_e32 v94, 0
	v_mov_b32_e32 v95, 0
	s_cbranch_execnz .LBB0_435
	s_branch .LBB0_434

; #define FLAS __attribute__((address_space(3)))
; __device__ __forceinline__ void attn_unit_a(FLAS unsigned char* lds, const Unit u) {
;     ...
;         if (i + 2 < NT) { *(FLAS u32x4*)(lds + LA_K + (i & 1) * KBUF + kdst) = kreg;
; #pragma unroll
;             for (int j = 0; j < 2; ++j) { *(FLAS u32x2*)(lds + LA_V + ((i + 2) & 3) * VBUF + vdst + j * 64 * VPITCH) = (u32x2){vreg[j].x, vreg[j].y}; *(FLAS u32x2*)(lds + LA_V + ((i + 2) & 3) * VBUF + vdst + j * 64 * VPITCH + 16) = (u32x2){vreg[j].z, vreg[j].w}; } }
;         __syncthreads();
;     };
;     for (int i = 0; i < NT; i += 2) { step(i, pa0, pa1, pb0, pb1, pwa, pwb); if (i + 1 < NT) step(i + 1, pb0, pb1, pa0, pa1, pwb, pwa); }
;     if (pend) {
; #pragma unroll
;         for (int d = 0; d < NDB; ++d) o[d] = o[d] * fpend; }
.LBB0_476:
	s_mov_b64 s[14:15], 0x100
	v_lshl_add_u64 v[228:229], v[228:229], 0, s[14:15]
	s_mov_b64 s[14:15], 0x60000
	v_cvt_pk_bf16_f32 v206, v68, v69
	v_cvt_pk_bf16_f32 v207, v70, v71
	s_addk_i32 s48, 0x80
	s_addk_i32 s49, 0x200
	v_lshl_add_u64 v[230:231], v[230:231], 0, s[14:15]
	s_mov_b64 s[24:25], 0
	s_and_b64 vcc, exec, s[4:5]
	v_cvt_pk_bf16_f32 v204, v64, v65
	v_cvt_pk_bf16_f32 v205, v66, v67
	s_waitcnt lgkmcnt(0)
	s_barrier
	s_cbranch_vccz .LBB0_433
	s_setprio 0
	s_andn2_b64 vcc, exec, s[0:1]
	s_cbranch_vccnz .LBB0_479
	v_pk_mul_f32 v[62:63], v[62:63], v[226:227] op_sel_hi:[1,0]
	v_pk_mul_f32 v[60:61], v[60:61], v[226:227] op_sel_hi:[1,0]
	v_pk_mul_f32 v[58:59], v[58:59], v[226:227] op_sel_hi:[1,0]
	v_pk_mul_f32 v[56:57], v[56:57], v[226:227] op_sel_hi:[1,0]
	v_pk_mul_f32 v[54:55], v[54:55], v[226:227] op_sel_hi:[1,0]
	v_pk_mul_f32 v[52:53], v[52:53], v[226:227] op_sel_hi:[1,0]
	v_pk_mul_f32 v[50:51], v[50:51], v[226:227] op_sel_hi:[1,0]
	v_pk_mul_f32 v[48:49], v[48:49], v[226:227] op_sel_hi:[1,0]
	v_pk_mul_f32 v[46:47], v[46:47], v[226:227] op_sel_hi:[1,0]
	v_pk_mul_f32 v[44:45], v[44:45], v[226:227] op_sel_hi:[1,0]
	v_pk_mul_f32 v[42:43], v[42:43], v[226:227] op_sel_hi:[1,0]
	v_pk_mul_f32 v[40:41], v[40:41], v[226:227] op_sel_hi:[1,0]
	v_pk_mul_f32 v[38:39], v[38:39], v[226:227] op_sel_hi:[1,0]
	v_pk_mul_f32 v[36:37], v[36:37], v[226:227] op_sel_hi:[1,0]
	v_pk_mul_f32 v[34:35], v[34:35], v[226:227] op_sel_hi:[1,0]
	v_pk_mul_f32 v[32:33], v[32:33], v[226:227] op_sel_hi:[1,0]
	v_pk_mul_f32 v[30:31], v[30:31], v[226:227] op_sel_hi:[1,0]
	v_pk_mul_f32 v[28:29], v[28:29], v[226:227] op_sel_hi:[1,0]
	v_pk_mul_f32 v[26:27], v[26:27], v[226:227] op_sel_hi:[1,0]
	v_pk_mul_f32 v[24:25], v[24:25], v[226:227] op_sel_hi:[1,0]
	v_pk_mul_f32 v[22:23], v[22:23], v[226:227] op_sel_hi:[1,0]
	v_pk_mul_f32 v[20:21], v[20:21], v[226:227] op_sel_hi:[1,0]
	v_pk_mul_f32 v[18:19], v[18:19], v[226:227] op_sel_hi:[1,0]
	v_pk_mul_f32 v[16:17], v[16:17], v[226:227] op_sel_hi:[1,0]
	v_pk_mul_f32 v[14:15], v[14:15], v[226:227] op_sel_hi:[1,0]
	v_pk_mul_f32 v[12:13], v[12:13], v[226:227] op_sel_hi:[1,0]
	v_pk_mul_f32 v[10:11], v[10:11], v[226:227] op_sel_hi:[1,0]
	v_pk_mul_f32 v[8:9], v[8:9], v[226:227] op_sel_hi:[1,0]
	v_pk_mul_f32 v[6:7], v[6:7], v[226:227] op_sel_hi:[1,0]
	v_pk_mul_f32 v[4:5], v[4:5], v[226:227] op_sel_hi:[1,0]
	v_pk_mul_f32 v[2:3], v[2:3], v[226:227] op_sel_hi:[1,0]
	v_pk_mul_f32 v[0:1], v[0:1], v[226:227] op_sel_hi:[1,0]
